# m9 + same 64-bit accumulator zeroing in the FFN-down and out-proj GEMM prologues (two code paths each)
# baseline (speedup 1.0000x reference)
.LBB0_516:
	v_lshl_add_u64 v[10:11], s[8:9], 0, v[188:189]
	v_mov_b32_e32 v131, v189
	v_and_b32_e32 v167, 15, v166
	v_and_b32_e32 v18, 48, v166
	v_lshlrev_b32_e32 v19, 2, v166
	v_lshl_add_u64 v[12:13], s[8:9], 0, v[130:131]
	s_and_b32 s21, s15, 3
	s_lshl_b32 s0, s20, 13
	v_lshl_or_b32 v18, v167, 6, v18
	v_and_b32_e32 v19, 32, v19
	s_add_i32 m0, s36, 0x18000
	v_lshl_add_u64 v[10:11], v[10:11], 0, s[4:5]
	v_lshl_add_u64 v[14:15], s[70:71], 0, v[188:189]
	s_lshl_b32 s35, s20, 6
	v_bitop3_b32 v20, v18, s0, v19 bitop3:0xde
	s_lshl_b32 s0, s21, 12
	s_waitcnt vmcnt(2)
	s_barrier
	global_load_lds_dwordx4 v[10:11], off
	v_lshl_add_u64 v[10:11], v[12:13], 0, s[4:5]
	s_add_i32 m0, s36, 0x1a000
	s_add_i32 s61, s36, 0x8000
	s_add_i32 s63, s36, 0xa000
	v_lshl_add_u64 v[16:17], s[70:71], 0, v[130:131]
	v_bitop3_b32 v140, v18, s0, v19 bitop3:0xde
	global_load_lds_dwordx4 v[10:11], off
	v_lshl_add_u64 v[10:11], v[14:15], 0, s[4:5]
	s_mov_b32 m0, s61
	s_add_u32 s0, s8, 0xb0080
	global_load_lds_dwordx4 v[10:11], off
	v_lshl_add_u64 v[10:11], v[16:17], 0, s[4:5]
	s_mov_b32 m0, s63
	s_addc_u32 s1, s9, 0
	global_load_lds_dwordx4 v[10:11], off
	s_add_i32 m0, s36, 0x1c000
	v_lshl_add_u64 v[10:11], s[0:1], 0, v[188:189]
	global_load_lds_dwordx4 v[10:11], off
	v_lshl_add_u64 v[10:11], s[0:1], 0, v[130:131]
	s_add_i32 m0, s36, 0x1e000
	s_movk_i32 s10, 0xb00
	global_load_lds_dwordx4 v[10:11], off
	v_lshrrev_b32_e32 v10, 1, v2
	v_mul_lo_u32 v2, v3, s10
	s_mov_b32 s11, 0xb000
	v_mad_u64_u32 v[2:3], s[0:1], v10, s11, v[2:3]
	v_or_b32_e32 v2, v2, v4
	v_add_lshl_u32 v132, v2, v5, 1
	v_lshrrev_b32_e32 v3, 1, v7
	v_mul_lo_u32 v2, v6, s10
	v_mad_u64_u32 v[2:3], s[0:1], v3, s11, v[2:3]
	s_waitcnt vmcnt(6)
	v_readlane_b32 s0, v252, 50
	v_or_b32_e32 v2, v2, v8
	v_mov_b32_e32 v50, 0
	s_mov_b32 s60, s0
	v_readlane_b32 s0, v251, 3
	v_or_b32_e32 v200, s35, v167
	v_mov_b32_e32 v133, v189
	v_add_lshl_u32 v134, v2, v9, 1
	v_mov_b32_e32 v135, v189
	s_mov_b32 s68, 0
	v_add_u32_e32 v141, 0, v20
	s_mov_b32 s19, s0
	v_mov_b64_e32 v[2:3], 0
	v_mov_b64_e32 v[4:5], 0
	v_mov_b64_e32 v[6:7], 0
	v_mov_b64_e32 v[8:9], 0
	v_mov_b64_e32 v[10:11], 0
	v_mov_b64_e32 v[12:13], 0
	v_mov_b64_e32 v[14:15], 0
	v_mov_b64_e32 v[16:17], 0
	v_mov_b64_e32 v[18:19], 0
	v_mov_b64_e32 v[20:21], 0
	v_mov_b64_e32 v[22:23], 0
	v_mov_b64_e32 v[24:25], 0
	v_mov_b64_e32 v[26:27], 0
	v_mov_b64_e32 v[28:29], 0
	v_mov_b64_e32 v[30:31], 0
	v_mov_b64_e32 v[32:33], 0
	v_mov_b64_e32 v[34:35], 0
	v_mov_b64_e32 v[36:37], 0
	v_mov_b64_e32 v[38:39], 0
	v_mov_b64_e32 v[40:41], 0
	v_mov_b64_e32 v[42:43], 0
	v_mov_b64_e32 v[44:45], 0
	v_mov_b64_e32 v[46:47], 0
	v_mov_b64_e32 v[48:49], 0
	v_mov_b64_e32 v[50:51], 0
	v_mov_b64_e32 v[52:53], 0
	v_mov_b64_e32 v[54:55], 0
	v_mov_b64_e32 v[56:57], 0
	v_mov_b64_e32 v[58:59], 0
	v_mov_b64_e32 v[60:61], 0
	v_mov_b64_e32 v[62:63], 0
	v_mov_b64_e32 v[64:65], 0
	v_mov_b64_e32 v[66:67], 0
	v_mov_b64_e32 v[68:69], 0
	v_mov_b64_e32 v[70:71], 0
	v_mov_b64_e32 v[72:73], 0
	v_mov_b64_e32 v[74:75], 0
	v_mov_b64_e32 v[76:77], 0
	v_mov_b64_e32 v[78:79], 0
	v_mov_b64_e32 v[80:81], 0
	v_mov_b64_e32 v[82:83], 0
	v_mov_b64_e32 v[84:85], 0
	v_mov_b64_e32 v[86:87], 0
	v_mov_b64_e32 v[88:89], 0
	v_mov_b64_e32 v[90:91], 0
	v_mov_b64_e32 v[92:93], 0
	v_mov_b64_e32 v[94:95], 0
	v_mov_b64_e32 v[96:97], 0
	v_mov_b64_e32 v[98:99], 0
	v_mov_b64_e32 v[100:101], 0
	v_mov_b64_e32 v[102:103], 0
	v_mov_b64_e32 v[104:105], 0
	v_mov_b64_e32 v[106:107], 0
	v_mov_b64_e32 v[108:109], 0
	v_mov_b64_e32 v[110:111], 0
	v_mov_b64_e32 v[112:113], 0
	v_mov_b64_e32 v[114:115], 0
	v_mov_b64_e32 v[116:117], 0
	v_mov_b64_e32 v[118:119], 0
	v_mov_b64_e32 v[120:121], 0
	v_mov_b64_e32 v[122:123], 0
	v_mov_b64_e32 v[124:125], 0
	v_mov_b64_e32 v[126:127], 0
	v_mov_b64_e32 v[128:129], 0
	s_barrier
	v_readlane_b32 s1, v251, 4

.LBB0_528:
	s_add_u32 s10, s70, s8
	s_addc_u32 s11, s71, s9
	s_add_u32 s10, s10, 0x100
	s_addc_u32 s11, s11, 0
	s_add_u32 s83, s80, s8
	s_addc_u32 s84, s81, s9
	s_add_i32 s85, 0, 0x10000
	s_cmpk_eq_i32 s8, 0x1500
	s_cselect_b32 s13, s1, s11
	s_cselect_b32 s12, s0, s10
	s_cselect_b32 s11, s45, s84
	s_cselect_b32 s10, s44, s83
	s_add_i32 s83, 0, 0x14000
	v_add_u32_e32 v154, s85, v140
	v_add_u32_e32 v172, s83, v140
	ds_read_b128 v[142:145], v154
	ds_read_b128 v[146:149], v154 offset:1024
	ds_read_b128 v[150:153], v154 offset:2048
	ds_read_b128 v[154:157], v154 offset:3072
	ds_read_b128 v[158:161], v172
	ds_read_b128 v[162:165], v172 offset:1024
	ds_read_b128 v[168:171], v172 offset:2048
	ds_read_b128 v[172:175], v172 offset:3072
	v_lshl_add_u64 v[184:185], v[138:139], 0, s[8:9]
	s_add_i32 m0, s36, 0xc000
	ds_read_b128 v[176:179], v141
	ds_read_b128 v[180:183], v141 offset:1024
	ds_read_b128 v[202:205], v141 offset:2048
	ds_read_b128 v[206:209], v141 offset:3072
	ds_read_b128 v[210:213], v141 offset:4096
	ds_read_b128 v[216:219], v141 offset:5120
	ds_read_b128 v[226:229], v141 offset:6144
	ds_read_b128 v[230:233], v141 offset:7168
	global_load_lds_dwordx4 v[184:185], off
	v_lshl_add_u64 v[184:185], v[136:137], 0, s[8:9]
	s_add_i32 m0, s36, 0xe000
	s_nop 0
	global_load_lds_dwordx4 v[184:185], off
	s_waitcnt vmcnt(8)
	s_waitcnt lgkmcnt(0)
	s_barrier
	s_setprio 1
	s_waitcnt lgkmcnt(0)
	v_mfma_f32_16x16x32_bf16 v[66:69], v[142:145], v[176:179], v[66:69]
	v_mfma_f32_16x16x32_bf16 v[34:37], v[150:153], v[176:179], v[34:37]
	v_mfma_f32_16x16x32_bf16 v[78:81], v[142:145], v[202:205], v[78:81]
	v_mfma_f32_16x16x32_bf16 v[46:49], v[150:153], v[202:205], v[46:49]
	v_mfma_f32_16x16x32_bf16 v[106:109], v[142:145], v[210:213], v[106:109]
	v_mfma_f32_16x16x32_bf16 v[62:65], v[150:153], v[210:213], v[62:65]
	v_mfma_f32_16x16x32_bf16 v[118:121], v[142:145], v[226:229], v[118:121]
	v_mfma_f32_16x16x32_bf16 v[74:77], v[150:153], v[226:229], v[74:77]
	v_mfma_f32_16x16x32_bf16 v[66:69], v[146:149], v[180:183], v[66:69]
	v_mfma_f32_16x16x32_bf16 v[34:37], v[154:157], v[180:183], v[34:37]
	v_mfma_f32_16x16x32_bf16 v[78:81], v[146:149], v[206:209], v[78:81]
	v_mfma_f32_16x16x32_bf16 v[46:49], v[154:157], v[206:209], v[46:49]
	v_mfma_f32_16x16x32_bf16 v[106:109], v[146:149], v[216:219], v[106:109]
	v_mfma_f32_16x16x32_bf16 v[62:65], v[154:157], v[216:219], v[62:65]
	v_mfma_f32_16x16x32_bf16 v[118:121], v[146:149], v[230:233], v[118:121]
	v_mfma_f32_16x16x32_bf16 v[74:77], v[154:157], v[230:233], v[74:77]
	s_setprio 0
	s_setprio 1
	v_mfma_f32_16x16x32_bf16 v[14:17], v[158:161], v[176:179], v[14:17]
	v_mfma_f32_16x16x32_bf16 v[2:5], v[168:171], v[176:179], v[2:5]
	v_mfma_f32_16x16x32_bf16 v[22:25], v[158:161], v[202:205], v[22:25]
	v_mfma_f32_16x16x32_bf16 v[6:9], v[168:171], v[202:205], v[6:9]
	v_mfma_f32_16x16x32_bf16 v[30:33], v[158:161], v[210:213], v[30:33]
	v_mfma_f32_16x16x32_bf16 v[10:13], v[168:171], v[210:213], v[10:13]
	v_mfma_f32_16x16x32_bf16 v[42:45], v[158:161], v[226:229], v[42:45]
	v_mfma_f32_16x16x32_bf16 v[18:21], v[168:171], v[226:229], v[18:21]
	v_mfma_f32_16x16x32_bf16 v[14:17], v[162:165], v[180:183], v[14:17]
	v_mfma_f32_16x16x32_bf16 v[2:5], v[172:175], v[180:183], v[2:5]
	v_mfma_f32_16x16x32_bf16 v[22:25], v[162:165], v[206:209], v[22:25]
	v_mfma_f32_16x16x32_bf16 v[6:9], v[172:175], v[206:209], v[6:9]
	v_mfma_f32_16x16x32_bf16 v[30:33], v[162:165], v[216:219], v[30:33]
	v_mfma_f32_16x16x32_bf16 v[10:13], v[172:175], v[216:219], v[10:13]
	v_mfma_f32_16x16x32_bf16 v[42:45], v[162:165], v[230:233], v[42:45]
	v_mfma_f32_16x16x32_bf16 v[18:21], v[172:175], v[230:233], v[18:21]
	s_setprio 0
	s_barrier
	s_add_i32 s84, s85, s24
	v_lshl_add_u64 v[184:185], s[10:11], 0, v[188:189]
	s_mov_b32 m0, s84
	ds_read_b128 v[176:179], v141 offset:16384
	ds_read_b128 v[180:183], v141 offset:17408
	ds_read_b128 v[202:205], v141 offset:18432
	ds_read_b128 v[206:209], v141 offset:19456
	ds_read_b128 v[210:213], v141 offset:20480
	ds_read_b128 v[216:219], v141 offset:21504
	ds_read_b128 v[226:229], v141 offset:22528
	ds_read_b128 v[230:233], v141 offset:23552
	global_load_lds_dwordx4 v[184:185], off
	s_add_i32 m0, s84, 0x2000
	s_add_u32 s84, s10, 0xb0000
	v_lshl_add_u64 v[234:235], s[10:11], 0, v[130:131]
	s_addc_u32 s85, s11, 0
	s_add_i32 s83, s83, s24
	global_load_lds_dwordx4 v[234:235], off
	v_lshl_add_u64 v[236:237], s[84:85], 0, v[188:189]
	s_mov_b32 m0, s83
	v_lshl_add_u64 v[238:239], s[12:13], 0, v[130:131]
	global_load_lds_dwordx4 v[236:237], off
	v_lshl_add_u64 v[236:237], s[84:85], 0, v[130:131]
	s_add_i32 m0, s83, 0x2000
	s_nop 0
	global_load_lds_dwordx4 v[236:237], off
	v_lshl_add_u64 v[236:237], s[12:13], 0, v[188:189]
	s_mov_b32 m0, s36
	s_nop 0
	global_load_lds_dwordx4 v[236:237], off
	s_mov_b32 m0, s37
	s_nop 0
	global_load_lds_dwordx4 v[238:239], off
	s_waitcnt vmcnt(8)
	s_waitcnt lgkmcnt(0)
	s_barrier
	s_setprio 1
	s_waitcnt lgkmcnt(0)
	v_mfma_f32_16x16x32_bf16 v[126:129], v[142:145], v[176:179], v[126:129]
	v_mfma_f32_16x16x32_bf16 v[98:101], v[150:153], v[176:179], v[98:101]
	v_mfma_f32_16x16x32_bf16 v[122:125], v[142:145], v[202:205], v[122:125]
	v_mfma_f32_16x16x32_bf16 v[114:117], v[150:153], v[202:205], v[114:117]
	v_mfma_f32_16x16x32_bf16 v[110:113], v[142:145], v[210:213], v[110:113]
	v_mfma_f32_16x16x32_bf16 v[102:105], v[150:153], v[210:213], v[102:105]
	v_mfma_f32_16x16x32_bf16 v[94:97], v[142:145], v[226:229], v[94:97]
	v_mfma_f32_16x16x32_bf16 v[90:93], v[150:153], v[226:229], v[90:93]
	v_mfma_f32_16x16x32_bf16 v[126:129], v[146:149], v[180:183], v[126:129]
	v_mfma_f32_16x16x32_bf16 v[98:101], v[154:157], v[180:183], v[98:101]
	v_mfma_f32_16x16x32_bf16 v[122:125], v[146:149], v[206:209], v[122:125]
	v_mfma_f32_16x16x32_bf16 v[114:117], v[154:157], v[206:209], v[114:117]
	v_mfma_f32_16x16x32_bf16 v[110:113], v[146:149], v[216:219], v[110:113]
	v_mfma_f32_16x16x32_bf16 v[102:105], v[154:157], v[216:219], v[102:105]
	v_mfma_f32_16x16x32_bf16 v[94:97], v[146:149], v[230:233], v[94:97]
	v_mfma_f32_16x16x32_bf16 v[90:93], v[154:157], v[230:233], v[90:93]
	s_setprio 0
	s_setprio 1
	v_mfma_f32_16x16x32_bf16 v[58:61], v[158:161], v[176:179], v[58:61]
	v_mfma_f32_16x16x32_bf16 v[26:29], v[168:171], v[176:179], v[26:29]
	v_mfma_f32_16x16x32_bf16 v[70:73], v[158:161], v[202:205], v[70:73]
	v_mfma_f32_16x16x32_bf16 v[38:41], v[168:171], v[202:205], v[38:41]
	v_mfma_f32_16x16x32_bf16 v[86:89], v[158:161], v[210:213], v[86:89]
	v_mfma_f32_16x16x32_bf16 v[54:57], v[168:171], v[210:213], v[54:57]
	v_mfma_f32_16x16x32_bf16 v[82:85], v[158:161], v[226:229], v[82:85]
	v_mfma_f32_16x16x32_bf16 v[50:53], v[168:171], v[226:229], v[50:53]
	v_mfma_f32_16x16x32_bf16 v[58:61], v[162:165], v[180:183], v[58:61]
	v_mfma_f32_16x16x32_bf16 v[26:29], v[172:175], v[180:183], v[26:29]
	v_mfma_f32_16x16x32_bf16 v[70:73], v[162:165], v[206:209], v[70:73]
	v_mfma_f32_16x16x32_bf16 v[38:41], v[172:175], v[206:209], v[38:41]
	v_mfma_f32_16x16x32_bf16 v[86:89], v[162:165], v[216:219], v[86:89]
	v_mfma_f32_16x16x32_bf16 v[54:57], v[172:175], v[216:219], v[54:57]
	v_mfma_f32_16x16x32_bf16 v[82:85], v[162:165], v[230:233], v[82:85]
	v_mfma_f32_16x16x32_bf16 v[50:53], v[172:175], v[230:233], v[50:53]
	s_setprio 0
	s_barrier
	s_add_i32 s83, 0, 0x18000
	s_add_i32 s84, 0, 0x1c000
	v_add_u32_e32 v154, s83, v140
	v_add_u32_e32 v172, s84, v140
	ds_read_b128 v[142:145], v154
	ds_read_b128 v[146:149], v154 offset:1024
	ds_read_b128 v[150:153], v154 offset:2048
	ds_read_b128 v[154:157], v154 offset:3072
	ds_read_b128 v[158:161], v172
	ds_read_b128 v[162:165], v172 offset:1024
	ds_read_b128 v[168:171], v172 offset:2048
	ds_read_b128 v[172:175], v172 offset:3072
	s_add_u32 s12, s12, 0xb0000
	s_addc_u32 s13, s13, 0
	s_mov_b32 m0, s54
	v_lshl_add_u64 v[240:241], s[12:13], 0, v[188:189]
	ds_read_b128 v[176:179], v141 offset:32768
	ds_read_b128 v[180:183], v141 offset:33792
	ds_read_b128 v[202:205], v141 offset:34816
	ds_read_b128 v[206:209], v141 offset:35840
	ds_read_b128 v[210:213], v141 offset:36864
	ds_read_b128 v[216:219], v141 offset:37888
	ds_read_b128 v[226:229], v141 offset:38912
	ds_read_b128 v[230:233], v141 offset:39936
	global_load_lds_dwordx4 v[240:241], off
	v_lshl_add_u64 v[240:241], s[12:13], 0, v[130:131]
	s_mov_b32 m0, s55
	s_nop 0
	global_load_lds_dwordx4 v[240:241], off
	s_waitcnt vmcnt(8)
	s_waitcnt lgkmcnt(0)
	s_barrier
	s_setprio 1
	s_waitcnt lgkmcnt(0)
	v_mfma_f32_16x16x32_bf16 v[66:69], v[142:145], v[176:179], v[66:69]
	v_mfma_f32_16x16x32_bf16 v[34:37], v[150:153], v[176:179], v[34:37]
	v_mfma_f32_16x16x32_bf16 v[78:81], v[142:145], v[202:205], v[78:81]
	v_mfma_f32_16x16x32_bf16 v[46:49], v[150:153], v[202:205], v[46:49]
	v_mfma_f32_16x16x32_bf16 v[106:109], v[142:145], v[210:213], v[106:109]
	v_mfma_f32_16x16x32_bf16 v[62:65], v[150:153], v[210:213], v[62:65]
	v_mfma_f32_16x16x32_bf16 v[118:121], v[142:145], v[226:229], v[118:121]
	v_mfma_f32_16x16x32_bf16 v[74:77], v[150:153], v[226:229], v[74:77]
	v_mfma_f32_16x16x32_bf16 v[66:69], v[146:149], v[180:183], v[66:69]
	v_mfma_f32_16x16x32_bf16 v[34:37], v[154:157], v[180:183], v[34:37]
	v_mfma_f32_16x16x32_bf16 v[78:81], v[146:149], v[206:209], v[78:81]
	v_mfma_f32_16x16x32_bf16 v[46:49], v[154:157], v[206:209], v[46:49]
	v_mfma_f32_16x16x32_bf16 v[106:109], v[146:149], v[216:219], v[106:109]
	v_mfma_f32_16x16x32_bf16 v[62:65], v[154:157], v[216:219], v[62:65]
	v_mfma_f32_16x16x32_bf16 v[118:121], v[146:149], v[230:233], v[118:121]
	v_mfma_f32_16x16x32_bf16 v[74:77], v[154:157], v[230:233], v[74:77]
	s_setprio 0
	s_setprio 1
	v_mfma_f32_16x16x32_bf16 v[14:17], v[158:161], v[176:179], v[14:17]
	v_mfma_f32_16x16x32_bf16 v[2:5], v[168:171], v[176:179], v[2:5]
	v_mfma_f32_16x16x32_bf16 v[22:25], v[158:161], v[202:205], v[22:25]
	v_mfma_f32_16x16x32_bf16 v[6:9], v[168:171], v[202:205], v[6:9]
	v_mfma_f32_16x16x32_bf16 v[30:33], v[158:161], v[210:213], v[30:33]
	v_mfma_f32_16x16x32_bf16 v[10:13], v[168:171], v[210:213], v[10:13]
	v_mfma_f32_16x16x32_bf16 v[42:45], v[158:161], v[226:229], v[42:45]
	v_mfma_f32_16x16x32_bf16 v[18:21], v[168:171], v[226:229], v[18:21]
	v_mfma_f32_16x16x32_bf16 v[14:17], v[162:165], v[180:183], v[14:17]
	v_mfma_f32_16x16x32_bf16 v[2:5], v[172:175], v[180:183], v[2:5]
	v_mfma_f32_16x16x32_bf16 v[22:25], v[162:165], v[206:209], v[22:25]
	v_mfma_f32_16x16x32_bf16 v[6:9], v[172:175], v[206:209], v[6:9]
	v_mfma_f32_16x16x32_bf16 v[30:33], v[162:165], v[216:219], v[30:33]
	v_mfma_f32_16x16x32_bf16 v[10:13], v[172:175], v[216:219], v[10:13]
	v_mfma_f32_16x16x32_bf16 v[42:45], v[162:165], v[230:233], v[42:45]
	v_mfma_f32_16x16x32_bf16 v[18:21], v[172:175], v[230:233], v[18:21]
	s_setprio 0
	s_barrier
	s_add_i32 s12, s83, s24
	v_lshl_add_u64 v[184:185], v[184:185], 0, s[4:5]
	s_mov_b32 m0, s12
	ds_read_b128 v[176:179], v141 offset:49152
	ds_read_b128 v[180:183], v141 offset:50176
	ds_read_b128 v[202:205], v141 offset:51200
	ds_read_b128 v[206:209], v141 offset:52224
	ds_read_b128 v[210:213], v141 offset:53248
	ds_read_b128 v[216:219], v141 offset:54272
	ds_read_b128 v[226:229], v141 offset:55296
	ds_read_b128 v[230:233], v141 offset:56320
	global_load_lds_dwordx4 v[184:185], off
	s_add_i32 m0, s12, 0x2000
	s_add_u32 s10, s10, 0xb0080
	v_lshl_add_u64 v[184:185], v[234:235], 0, s[4:5]
	s_addc_u32 s11, s11, 0
	s_add_i32 s12, s84, s24
	global_load_lds_dwordx4 v[184:185], off
	v_lshl_add_u64 v[184:185], s[10:11], 0, v[188:189]
	s_mov_b32 m0, s12
	s_nop 0
	global_load_lds_dwordx4 v[184:185], off
	v_lshl_add_u64 v[184:185], s[10:11], 0, v[130:131]
	s_add_i32 m0, s12, 0x2000
	s_nop 0
	global_load_lds_dwordx4 v[184:185], off
	v_lshl_add_u64 v[184:185], v[236:237], 0, s[4:5]
	s_mov_b32 m0, s61
	s_nop 0
	global_load_lds_dwordx4 v[184:185], off
	v_lshl_add_u64 v[184:185], v[238:239], 0, s[4:5]
	s_mov_b32 m0, s63
	s_nop 0
	global_load_lds_dwordx4 v[184:185], off
	s_waitcnt vmcnt(8)
	s_waitcnt lgkmcnt(0)
	s_barrier
	s_setprio 1
	s_waitcnt lgkmcnt(0)
	v_mfma_f32_16x16x32_bf16 v[126:129], v[142:145], v[176:179], v[126:129]
	v_mfma_f32_16x16x32_bf16 v[98:101], v[150:153], v[176:179], v[98:101]
	v_mfma_f32_16x16x32_bf16 v[122:125], v[142:145], v[202:205], v[122:125]
	v_mfma_f32_16x16x32_bf16 v[114:117], v[150:153], v[202:205], v[114:117]
	v_mfma_f32_16x16x32_bf16 v[110:113], v[142:145], v[210:213], v[110:113]
	v_mfma_f32_16x16x32_bf16 v[102:105], v[150:153], v[210:213], v[102:105]
	v_mfma_f32_16x16x32_bf16 v[94:97], v[142:145], v[226:229], v[94:97]
	v_mfma_f32_16x16x32_bf16 v[90:93], v[150:153], v[226:229], v[90:93]
	v_mfma_f32_16x16x32_bf16 v[126:129], v[146:149], v[180:183], v[126:129]
	v_mfma_f32_16x16x32_bf16 v[98:101], v[154:157], v[180:183], v[98:101]
	v_mfma_f32_16x16x32_bf16 v[122:125], v[146:149], v[206:209], v[122:125]
	v_mfma_f32_16x16x32_bf16 v[114:117], v[154:157], v[206:209], v[114:117]
	v_mfma_f32_16x16x32_bf16 v[110:113], v[146:149], v[216:219], v[110:113]
	v_mfma_f32_16x16x32_bf16 v[102:105], v[154:157], v[216:219], v[102:105]
	v_mfma_f32_16x16x32_bf16 v[94:97], v[146:149], v[230:233], v[94:97]
	v_mfma_f32_16x16x32_bf16 v[90:93], v[154:157], v[230:233], v[90:93]
	s_setprio 0
	s_setprio 1
	v_mfma_f32_16x16x32_bf16 v[58:61], v[158:161], v[176:179], v[58:61]
	v_mfma_f32_16x16x32_bf16 v[26:29], v[168:171], v[176:179], v[26:29]
	v_mfma_f32_16x16x32_bf16 v[70:73], v[158:161], v[202:205], v[70:73]
	v_mfma_f32_16x16x32_bf16 v[38:41], v[168:171], v[202:205], v[38:41]
	v_mfma_f32_16x16x32_bf16 v[86:89], v[158:161], v[210:213], v[86:89]
	v_mfma_f32_16x16x32_bf16 v[54:57], v[168:171], v[210:213], v[54:57]
	v_mfma_f32_16x16x32_bf16 v[82:85], v[158:161], v[226:229], v[82:85]
	v_mfma_f32_16x16x32_bf16 v[50:53], v[168:171], v[226:229], v[50:53]
	v_mfma_f32_16x16x32_bf16 v[58:61], v[162:165], v[180:183], v[58:61]
	v_mfma_f32_16x16x32_bf16 v[26:29], v[172:175], v[180:183], v[26:29]
	v_mfma_f32_16x16x32_bf16 v[70:73], v[162:165], v[206:209], v[70:73]
	v_mfma_f32_16x16x32_bf16 v[38:41], v[172:175], v[206:209], v[38:41]
	v_mfma_f32_16x16x32_bf16 v[86:89], v[162:165], v[216:219], v[86:89]
	v_mfma_f32_16x16x32_bf16 v[54:57], v[172:175], v[216:219], v[54:57]
	v_mfma_f32_16x16x32_bf16 v[82:85], v[162:165], v[230:233], v[82:85]
	v_mfma_f32_16x16x32_bf16 v[50:53], v[172:175], v[230:233], v[50:53]
	s_setprio 0
	s_barrier
	s_add_i32 s82, s82, 2
	s_add_u32 s8, s8, 0x100
	s_addc_u32 s9, s9, 0
	s_cmp_gt_u32 s82, 41
	s_cbranch_scc0 .LBB0_528
	s_add_u32 s8, s80, 0xffffff00
	s_addc_u32 s9, s81, -1
	s_and_b64 vcc, exec, s[42:43]
	s_cbranch_vccnz .LBB0_531
	v_mov_b32_e32 v50, 0
	s_mov_b32 s60, s77
	s_mov_b32 s19, s78
	s_mov_b64 s[70:71], s[0:1]
	s_mov_b32 s68, s79
	v_mov_b64_e32 v[2:3], 0
	v_mov_b64_e32 v[4:5], 0
	v_mov_b64_e32 v[6:7], 0
	v_mov_b64_e32 v[8:9], 0
	v_mov_b64_e32 v[10:11], 0
	v_mov_b64_e32 v[12:13], 0
	v_mov_b64_e32 v[14:15], 0
	v_mov_b64_e32 v[16:17], 0
	v_mov_b64_e32 v[18:19], 0
	v_mov_b64_e32 v[20:21], 0
	v_mov_b64_e32 v[22:23], 0
	v_mov_b64_e32 v[24:25], 0
	v_mov_b64_e32 v[26:27], 0
	v_mov_b64_e32 v[28:29], 0
	v_mov_b64_e32 v[30:31], 0
	v_mov_b64_e32 v[32:33], 0
	v_mov_b64_e32 v[34:35], 0
	v_mov_b64_e32 v[36:37], 0
	v_mov_b64_e32 v[38:39], 0
	v_mov_b64_e32 v[40:41], 0
	v_mov_b64_e32 v[42:43], 0
	v_mov_b64_e32 v[44:45], 0
	v_mov_b64_e32 v[46:47], 0
	v_mov_b64_e32 v[48:49], 0
	v_mov_b64_e32 v[50:51], 0
	v_mov_b64_e32 v[52:53], 0
	v_mov_b64_e32 v[54:55], 0
	v_mov_b64_e32 v[56:57], 0
	v_mov_b64_e32 v[58:59], 0
	v_mov_b64_e32 v[60:61], 0
	v_mov_b64_e32 v[62:63], 0
	v_mov_b64_e32 v[64:65], 0
	v_mov_b64_e32 v[66:67], 0
	v_mov_b64_e32 v[68:69], 0
	v_mov_b64_e32 v[70:71], 0
	v_mov_b64_e32 v[72:73], 0
	v_mov_b64_e32 v[74:75], 0
	v_mov_b64_e32 v[76:77], 0
	v_mov_b64_e32 v[78:79], 0
	v_mov_b64_e32 v[80:81], 0
	v_mov_b64_e32 v[82:83], 0
	v_mov_b64_e32 v[84:85], 0
	v_mov_b64_e32 v[86:87], 0
	v_mov_b64_e32 v[88:89], 0
	v_mov_b64_e32 v[90:91], 0
	v_mov_b64_e32 v[92:93], 0
	v_mov_b64_e32 v[94:95], 0
	v_mov_b64_e32 v[96:97], 0
	v_mov_b64_e32 v[98:99], 0
	v_mov_b64_e32 v[100:101], 0
	v_mov_b64_e32 v[102:103], 0
	v_mov_b64_e32 v[104:105], 0
	v_mov_b64_e32 v[106:107], 0
	v_mov_b64_e32 v[108:109], 0
	v_mov_b64_e32 v[110:111], 0
	v_mov_b64_e32 v[112:113], 0
	v_mov_b64_e32 v[114:115], 0
	v_mov_b64_e32 v[116:117], 0
	v_mov_b64_e32 v[118:119], 0
	v_mov_b64_e32 v[120:121], 0
	v_mov_b64_e32 v[122:123], 0
	v_mov_b64_e32 v[124:125], 0
	v_mov_b64_e32 v[126:127], 0
	v_mov_b64_e32 v[128:129], 0
	s_branch .LBB0_532

.LBB0_3218:
	v_lshl_add_u64 v[10:11], s[8:9], 0, v[188:189]
	v_mov_b32_e32 v131, v189
	v_and_b32_e32 v168, 15, v167
	v_and_b32_e32 v18, 48, v167
	v_lshlrev_b32_e32 v19, 2, v167
	v_lshl_add_u64 v[12:13], s[8:9], 0, v[130:131]
	s_and_b32 s18, s15, 3
	s_lshl_b32 s0, s17, 13
	v_lshl_or_b32 v18, v168, 6, v18
	v_and_b32_e32 v19, 32, v19
	s_add_i32 m0, s29, 0x18000
	v_lshl_add_u64 v[10:11], v[10:11], 0, s[4:5]
	v_lshl_add_u64 v[14:15], s[52:53], 0, v[188:189]
	s_lshl_b32 s20, s17, 6
	v_bitop3_b32 v20, v18, s0, v19 bitop3:0xde
	s_lshl_b32 s0, s18, 12
	s_waitcnt vmcnt(2)
	s_barrier
	global_load_lds_dwordx4 v[10:11], off
	v_lshl_add_u64 v[10:11], v[12:13], 0, s[4:5]
	s_add_i32 m0, s29, 0x1a000
	s_add_i32 s37, s29, 0x8000
	s_add_i32 s43, s29, 0xa000
	v_lshl_add_u64 v[16:17], s[52:53], 0, v[130:131]
	v_bitop3_b32 v140, v18, s0, v19 bitop3:0xde
	global_load_lds_dwordx4 v[10:11], off
	v_lshl_add_u64 v[10:11], v[14:15], 0, s[4:5]
	s_mov_b32 m0, s37
	s_add_u32 s0, s8, 0x40080
	global_load_lds_dwordx4 v[10:11], off
	v_lshl_add_u64 v[10:11], v[16:17], 0, s[4:5]
	s_mov_b32 m0, s43
	s_addc_u32 s1, s9, 0
	global_load_lds_dwordx4 v[10:11], off
	s_add_i32 m0, s29, 0x1c000
	v_lshl_add_u64 v[10:11], s[0:1], 0, v[188:189]
	global_load_lds_dwordx4 v[10:11], off
	v_lshl_add_u64 v[10:11], s[0:1], 0, v[130:131]
	s_add_i32 m0, s29, 0x1e000
	v_lshlrev_b32_e32 v2, 13, v2
	global_load_lds_dwordx4 v[10:11], off
	v_and_b32_e32 v2, 0x7fffc000, v2
	v_lshl_add_u32 v2, v3, 10, v2
	v_or_b32_e32 v2, v2, v4
	v_add_lshl_u32 v132, v2, v5, 1
	v_lshlrev_b32_e32 v2, 13, v7
	v_and_b32_e32 v2, 0x7fffc000, v2
	s_waitcnt vmcnt(6)
	v_lshl_add_u32 v2, v6, 10, v2
	v_readlane_b32 s0, v252, 50
	v_or_b32_e32 v2, v2, v8
	v_mov_b32_e32 v30, 0
	s_mov_b32 s42, s0
	v_readlane_b32 s0, v251, 3
	v_or_b32_e32 v166, s20, v168
	v_mov_b32_e32 v133, v189
	v_add_lshl_u32 v134, v2, v9, 1
	v_mov_b32_e32 v135, v189
	s_mov_b32 s55, 0
	v_add_u32_e32 v141, 0, v20
	s_mov_b32 s16, s0
	v_mov_b64_e32 v[2:3], 0
	v_mov_b64_e32 v[4:5], 0
	v_mov_b64_e32 v[6:7], 0
	v_mov_b64_e32 v[8:9], 0
	v_mov_b64_e32 v[10:11], 0
	v_mov_b64_e32 v[12:13], 0
	v_mov_b64_e32 v[14:15], 0
	v_mov_b64_e32 v[16:17], 0
	v_mov_b64_e32 v[18:19], 0
	v_mov_b64_e32 v[20:21], 0
	v_mov_b64_e32 v[22:23], 0
	v_mov_b64_e32 v[24:25], 0
	v_mov_b64_e32 v[26:27], 0
	v_mov_b64_e32 v[28:29], 0
	v_mov_b64_e32 v[30:31], 0
	v_mov_b64_e32 v[32:33], 0
	v_mov_b64_e32 v[34:35], 0
	v_mov_b64_e32 v[36:37], 0
	v_mov_b64_e32 v[38:39], 0
	v_mov_b64_e32 v[40:41], 0
	v_mov_b64_e32 v[42:43], 0
	v_mov_b64_e32 v[44:45], 0
	v_mov_b64_e32 v[46:47], 0
	v_mov_b64_e32 v[48:49], 0
	v_mov_b64_e32 v[50:51], 0
	v_mov_b64_e32 v[52:53], 0
	v_mov_b64_e32 v[54:55], 0
	v_mov_b64_e32 v[56:57], 0
	v_mov_b64_e32 v[58:59], 0
	v_mov_b64_e32 v[60:61], 0
	v_mov_b64_e32 v[62:63], 0
	v_mov_b64_e32 v[64:65], 0
	v_mov_b64_e32 v[66:67], 0
	v_mov_b64_e32 v[68:69], 0
	v_mov_b64_e32 v[70:71], 0
	v_mov_b64_e32 v[72:73], 0
	v_mov_b64_e32 v[74:75], 0
	v_mov_b64_e32 v[76:77], 0
	v_mov_b64_e32 v[78:79], 0
	v_mov_b64_e32 v[80:81], 0
	v_mov_b64_e32 v[82:83], 0
	v_mov_b64_e32 v[84:85], 0
	v_mov_b64_e32 v[86:87], 0
	v_mov_b64_e32 v[88:89], 0
	v_mov_b64_e32 v[90:91], 0
	v_mov_b64_e32 v[92:93], 0
	v_mov_b64_e32 v[94:95], 0
	v_mov_b64_e32 v[96:97], 0
	v_mov_b64_e32 v[98:99], 0
	v_mov_b64_e32 v[100:101], 0
	v_mov_b64_e32 v[102:103], 0
	v_mov_b64_e32 v[104:105], 0
	v_mov_b64_e32 v[106:107], 0
	v_mov_b64_e32 v[108:109], 0
	v_mov_b64_e32 v[110:111], 0
	v_mov_b64_e32 v[112:113], 0
	v_mov_b64_e32 v[114:115], 0
	v_mov_b64_e32 v[116:117], 0
	v_mov_b64_e32 v[118:119], 0
	v_mov_b64_e32 v[120:121], 0
	v_mov_b64_e32 v[122:123], 0
	v_mov_b64_e32 v[124:125], 0
	v_mov_b64_e32 v[126:127], 0
	v_mov_b64_e32 v[128:129], 0
	s_barrier
	v_readlane_b32 s1, v251, 4
	s_branch .LBB0_3221

.LBB0_3228:
	s_add_u32 s10, s52, s8
	s_addc_u32 s11, s53, s9
	s_add_u32 s10, s10, 0x100
	s_addc_u32 s11, s11, 0
	s_add_u32 s71, s63, s8
	s_addc_u32 s77, s64, s9
	s_add_i32 s78, 0, 0x10000
	s_cmpk_eq_i32 s8, 0x700
	s_cselect_b32 s13, s59, s11
	s_cselect_b32 s12, s65, s10
	s_cselect_b32 s11, s57, s77
	s_cselect_b32 s10, s68, s71
	s_add_i32 s71, 0, 0x14000
	v_add_u32_e32 v154, s78, v140
	v_add_u32_e32 v169, s71, v140
	ds_read_b128 v[142:145], v154
	ds_read_b128 v[146:149], v154 offset:1024
	ds_read_b128 v[150:153], v154 offset:2048
	ds_read_b128 v[154:157], v154 offset:3072
	ds_read_b128 v[158:161], v169
	ds_read_b128 v[162:165], v169 offset:1024
	ds_read_b128 v[170:173], v169 offset:2048
	ds_read_b128 v[174:177], v169 offset:3072
	v_lshl_add_u64 v[230:231], v[138:139], 0, s[8:9]
	s_add_i32 m0, s29, 0xc000
	ds_read_b128 v[178:181], v141
	ds_read_b128 v[182:185], v141 offset:1024
	ds_read_b128 v[200:203], v141 offset:2048
	ds_read_b128 v[204:207], v141 offset:3072
	ds_read_b128 v[208:211], v141 offset:4096
	ds_read_b128 v[212:215], v141 offset:5120
	ds_read_b128 v[216:219], v141 offset:6144
	ds_read_b128 v[226:229], v141 offset:7168
	global_load_lds_dwordx4 v[230:231], off
	v_lshl_add_u64 v[230:231], v[136:137], 0, s[8:9]
	s_add_i32 m0, s29, 0xe000
	s_nop 0
	global_load_lds_dwordx4 v[230:231], off
	s_waitcnt vmcnt(8)
	s_waitcnt lgkmcnt(0)
	s_barrier
	s_setprio 1
	s_waitcnt lgkmcnt(0)
	v_mfma_f32_16x16x32_bf16 v[126:129], v[142:145], v[178:181], v[126:129]
	v_mfma_f32_16x16x32_bf16 v[66:69], v[150:153], v[178:181], v[66:69]
	v_mfma_f32_16x16x32_bf16 v[122:125], v[142:145], v[200:203], v[122:125]
	v_mfma_f32_16x16x32_bf16 v[70:73], v[150:153], v[200:203], v[70:73]
	v_mfma_f32_16x16x32_bf16 v[118:121], v[142:145], v[208:211], v[118:121]
	v_mfma_f32_16x16x32_bf16 v[74:77], v[150:153], v[208:211], v[74:77]
	v_mfma_f32_16x16x32_bf16 v[114:117], v[142:145], v[216:219], v[114:117]
	v_mfma_f32_16x16x32_bf16 v[78:81], v[150:153], v[216:219], v[78:81]
	v_mfma_f32_16x16x32_bf16 v[126:129], v[146:149], v[182:185], v[126:129]
	v_mfma_f32_16x16x32_bf16 v[66:69], v[154:157], v[182:185], v[66:69]
	v_mfma_f32_16x16x32_bf16 v[122:125], v[146:149], v[204:207], v[122:125]
	v_mfma_f32_16x16x32_bf16 v[70:73], v[154:157], v[204:207], v[70:73]
	v_mfma_f32_16x16x32_bf16 v[118:121], v[146:149], v[212:215], v[118:121]
	v_mfma_f32_16x16x32_bf16 v[74:77], v[154:157], v[212:215], v[74:77]
	v_mfma_f32_16x16x32_bf16 v[114:117], v[146:149], v[226:229], v[114:117]
	v_mfma_f32_16x16x32_bf16 v[78:81], v[154:157], v[226:229], v[78:81]
	s_setprio 0
	s_setprio 1
	v_mfma_f32_16x16x32_bf16 v[34:37], v[158:161], v[178:181], v[34:37]
	v_mfma_f32_16x16x32_bf16 v[2:5], v[170:173], v[178:181], v[2:5]
	v_mfma_f32_16x16x32_bf16 v[38:41], v[158:161], v[200:203], v[38:41]
	v_mfma_f32_16x16x32_bf16 v[6:9], v[170:173], v[200:203], v[6:9]
	v_mfma_f32_16x16x32_bf16 v[42:45], v[158:161], v[208:211], v[42:45]
	v_mfma_f32_16x16x32_bf16 v[10:13], v[170:173], v[208:211], v[10:13]
	v_mfma_f32_16x16x32_bf16 v[46:49], v[158:161], v[216:219], v[46:49]
	v_mfma_f32_16x16x32_bf16 v[14:17], v[170:173], v[216:219], v[14:17]
	v_mfma_f32_16x16x32_bf16 v[34:37], v[162:165], v[182:185], v[34:37]
	v_mfma_f32_16x16x32_bf16 v[2:5], v[174:177], v[182:185], v[2:5]
	v_mfma_f32_16x16x32_bf16 v[38:41], v[162:165], v[204:207], v[38:41]
	v_mfma_f32_16x16x32_bf16 v[6:9], v[174:177], v[204:207], v[6:9]
	v_mfma_f32_16x16x32_bf16 v[42:45], v[162:165], v[212:215], v[42:45]
	v_mfma_f32_16x16x32_bf16 v[10:13], v[174:177], v[212:215], v[10:13]
	v_mfma_f32_16x16x32_bf16 v[46:49], v[162:165], v[226:229], v[46:49]
	v_mfma_f32_16x16x32_bf16 v[14:17], v[174:177], v[226:229], v[14:17]
	s_setprio 0
	s_barrier
	s_add_i32 s77, s78, s19
	v_lshl_add_u64 v[230:231], s[10:11], 0, v[188:189]
	s_mov_b32 m0, s77
	ds_read_b128 v[178:181], v141 offset:16384
	ds_read_b128 v[182:185], v141 offset:17408
	ds_read_b128 v[200:203], v141 offset:18432
	ds_read_b128 v[204:207], v141 offset:19456
	ds_read_b128 v[208:211], v141 offset:20480
	ds_read_b128 v[212:215], v141 offset:21504
	ds_read_b128 v[216:219], v141 offset:22528
	ds_read_b128 v[226:229], v141 offset:23552
	global_load_lds_dwordx4 v[230:231], off
	s_add_i32 m0, s77, 0x2000
	s_add_u32 s78, s10, 0x40000
	v_lshl_add_u64 v[232:233], s[10:11], 0, v[130:131]
	s_addc_u32 s79, s11, 0
	s_add_i32 s71, s71, s19
	global_load_lds_dwordx4 v[232:233], off
	v_lshl_add_u64 v[234:235], s[78:79], 0, v[188:189]
	s_mov_b32 m0, s71
	v_lshl_add_u64 v[236:237], s[12:13], 0, v[130:131]
	global_load_lds_dwordx4 v[234:235], off
	v_lshl_add_u64 v[234:235], s[78:79], 0, v[130:131]
	s_add_i32 m0, s71, 0x2000
	s_nop 0
	global_load_lds_dwordx4 v[234:235], off
	v_lshl_add_u64 v[234:235], s[12:13], 0, v[188:189]
	s_mov_b32 m0, s29
	s_nop 0
	global_load_lds_dwordx4 v[234:235], off
	s_mov_b32 m0, s34
	s_nop 0
	global_load_lds_dwordx4 v[236:237], off
	s_waitcnt vmcnt(8)
	s_waitcnt lgkmcnt(0)
	s_barrier
	s_setprio 1
	s_waitcnt lgkmcnt(0)
	v_mfma_f32_16x16x32_bf16 v[106:109], v[142:145], v[178:181], v[106:109]
	v_mfma_f32_16x16x32_bf16 v[82:85], v[150:153], v[178:181], v[82:85]
	v_mfma_f32_16x16x32_bf16 v[110:113], v[142:145], v[200:203], v[110:113]
	v_mfma_f32_16x16x32_bf16 v[86:89], v[150:153], v[200:203], v[86:89]
	v_mfma_f32_16x16x32_bf16 v[102:105], v[142:145], v[208:211], v[102:105]
	v_mfma_f32_16x16x32_bf16 v[90:93], v[150:153], v[208:211], v[90:93]
	v_mfma_f32_16x16x32_bf16 v[98:101], v[142:145], v[216:219], v[98:101]
	v_mfma_f32_16x16x32_bf16 v[94:97], v[150:153], v[216:219], v[94:97]
	v_mfma_f32_16x16x32_bf16 v[106:109], v[146:149], v[182:185], v[106:109]
	v_mfma_f32_16x16x32_bf16 v[82:85], v[154:157], v[182:185], v[82:85]
	v_mfma_f32_16x16x32_bf16 v[110:113], v[146:149], v[204:207], v[110:113]
	v_mfma_f32_16x16x32_bf16 v[86:89], v[154:157], v[204:207], v[86:89]
	v_mfma_f32_16x16x32_bf16 v[102:105], v[146:149], v[212:215], v[102:105]
	v_mfma_f32_16x16x32_bf16 v[90:93], v[154:157], v[212:215], v[90:93]
	v_mfma_f32_16x16x32_bf16 v[98:101], v[146:149], v[226:229], v[98:101]
	v_mfma_f32_16x16x32_bf16 v[94:97], v[154:157], v[226:229], v[94:97]
	s_setprio 0
	s_setprio 1
	v_mfma_f32_16x16x32_bf16 v[50:53], v[158:161], v[178:181], v[50:53]
	v_mfma_f32_16x16x32_bf16 v[18:21], v[170:173], v[178:181], v[18:21]
	v_mfma_f32_16x16x32_bf16 v[54:57], v[158:161], v[200:203], v[54:57]
	v_mfma_f32_16x16x32_bf16 v[22:25], v[170:173], v[200:203], v[22:25]
	v_mfma_f32_16x16x32_bf16 v[58:61], v[158:161], v[208:211], v[58:61]
	v_mfma_f32_16x16x32_bf16 v[26:29], v[170:173], v[208:211], v[26:29]
	v_mfma_f32_16x16x32_bf16 v[62:65], v[158:161], v[216:219], v[62:65]
	v_mfma_f32_16x16x32_bf16 v[30:33], v[170:173], v[216:219], v[30:33]
	v_mfma_f32_16x16x32_bf16 v[50:53], v[162:165], v[182:185], v[50:53]
	v_mfma_f32_16x16x32_bf16 v[18:21], v[174:177], v[182:185], v[18:21]
	v_mfma_f32_16x16x32_bf16 v[54:57], v[162:165], v[204:207], v[54:57]
	v_mfma_f32_16x16x32_bf16 v[22:25], v[174:177], v[204:207], v[22:25]
	v_mfma_f32_16x16x32_bf16 v[58:61], v[162:165], v[212:215], v[58:61]
	v_mfma_f32_16x16x32_bf16 v[26:29], v[174:177], v[212:215], v[26:29]
	v_mfma_f32_16x16x32_bf16 v[62:65], v[162:165], v[226:229], v[62:65]
	v_mfma_f32_16x16x32_bf16 v[30:33], v[174:177], v[226:229], v[30:33]
	s_setprio 0
	s_barrier
	s_add_i32 s71, 0, 0x18000
	s_add_i32 s77, 0, 0x1c000
	v_add_u32_e32 v154, s71, v140
	v_add_u32_e32 v169, s77, v140
	ds_read_b128 v[142:145], v154
	ds_read_b128 v[146:149], v154 offset:1024
	ds_read_b128 v[150:153], v154 offset:2048
	ds_read_b128 v[154:157], v154 offset:3072
	ds_read_b128 v[158:161], v169
	ds_read_b128 v[162:165], v169 offset:1024
	ds_read_b128 v[170:173], v169 offset:2048
	ds_read_b128 v[174:177], v169 offset:3072
	s_add_u32 s12, s12, 0x40000
	s_addc_u32 s13, s13, 0
	s_mov_b32 m0, s35
	v_lshl_add_u64 v[238:239], s[12:13], 0, v[188:189]
	ds_read_b128 v[178:181], v141 offset:32768
	ds_read_b128 v[182:185], v141 offset:33792
	ds_read_b128 v[200:203], v141 offset:34816
	ds_read_b128 v[204:207], v141 offset:35840
	ds_read_b128 v[208:211], v141 offset:36864
	ds_read_b128 v[212:215], v141 offset:37888
	ds_read_b128 v[216:219], v141 offset:38912
	ds_read_b128 v[226:229], v141 offset:39936
	global_load_lds_dwordx4 v[238:239], off
	v_lshl_add_u64 v[238:239], s[12:13], 0, v[130:131]
	s_mov_b32 m0, s36
	s_nop 0
	global_load_lds_dwordx4 v[238:239], off
	s_waitcnt vmcnt(8)
	s_waitcnt lgkmcnt(0)
	s_barrier
	s_setprio 1
	s_waitcnt lgkmcnt(0)
	v_mfma_f32_16x16x32_bf16 v[126:129], v[142:145], v[178:181], v[126:129]
	v_mfma_f32_16x16x32_bf16 v[66:69], v[150:153], v[178:181], v[66:69]
	v_mfma_f32_16x16x32_bf16 v[122:125], v[142:145], v[200:203], v[122:125]
	v_mfma_f32_16x16x32_bf16 v[70:73], v[150:153], v[200:203], v[70:73]
	v_mfma_f32_16x16x32_bf16 v[118:121], v[142:145], v[208:211], v[118:121]
	v_mfma_f32_16x16x32_bf16 v[74:77], v[150:153], v[208:211], v[74:77]
	v_mfma_f32_16x16x32_bf16 v[114:117], v[142:145], v[216:219], v[114:117]
	v_mfma_f32_16x16x32_bf16 v[78:81], v[150:153], v[216:219], v[78:81]
	v_mfma_f32_16x16x32_bf16 v[126:129], v[146:149], v[182:185], v[126:129]
	v_mfma_f32_16x16x32_bf16 v[66:69], v[154:157], v[182:185], v[66:69]
	v_mfma_f32_16x16x32_bf16 v[122:125], v[146:149], v[204:207], v[122:125]
	v_mfma_f32_16x16x32_bf16 v[70:73], v[154:157], v[204:207], v[70:73]
	v_mfma_f32_16x16x32_bf16 v[118:121], v[146:149], v[212:215], v[118:121]
	v_mfma_f32_16x16x32_bf16 v[74:77], v[154:157], v[212:215], v[74:77]
	v_mfma_f32_16x16x32_bf16 v[114:117], v[146:149], v[226:229], v[114:117]
	v_mfma_f32_16x16x32_bf16 v[78:81], v[154:157], v[226:229], v[78:81]
	s_setprio 0
	s_setprio 1
	v_mfma_f32_16x16x32_bf16 v[34:37], v[158:161], v[178:181], v[34:37]
	v_mfma_f32_16x16x32_bf16 v[2:5], v[170:173], v[178:181], v[2:5]
	v_mfma_f32_16x16x32_bf16 v[38:41], v[158:161], v[200:203], v[38:41]
	v_mfma_f32_16x16x32_bf16 v[6:9], v[170:173], v[200:203], v[6:9]
	v_mfma_f32_16x16x32_bf16 v[42:45], v[158:161], v[208:211], v[42:45]
	v_mfma_f32_16x16x32_bf16 v[10:13], v[170:173], v[208:211], v[10:13]
	v_mfma_f32_16x16x32_bf16 v[46:49], v[158:161], v[216:219], v[46:49]
	v_mfma_f32_16x16x32_bf16 v[14:17], v[170:173], v[216:219], v[14:17]
	v_mfma_f32_16x16x32_bf16 v[34:37], v[162:165], v[182:185], v[34:37]
	v_mfma_f32_16x16x32_bf16 v[2:5], v[174:177], v[182:185], v[2:5]
	v_mfma_f32_16x16x32_bf16 v[38:41], v[162:165], v[204:207], v[38:41]
	v_mfma_f32_16x16x32_bf16 v[6:9], v[174:177], v[204:207], v[6:9]
	v_mfma_f32_16x16x32_bf16 v[42:45], v[162:165], v[212:215], v[42:45]
	v_mfma_f32_16x16x32_bf16 v[10:13], v[174:177], v[212:215], v[10:13]
	v_mfma_f32_16x16x32_bf16 v[46:49], v[162:165], v[226:229], v[46:49]
	v_mfma_f32_16x16x32_bf16 v[14:17], v[174:177], v[226:229], v[14:17]
	s_setprio 0
	s_barrier
	s_add_i32 s12, s71, s19
	v_lshl_add_u64 v[230:231], v[230:231], 0, s[4:5]
	s_mov_b32 m0, s12
	ds_read_b128 v[178:181], v141 offset:49152
	ds_read_b128 v[182:185], v141 offset:50176
	ds_read_b128 v[200:203], v141 offset:51200
	ds_read_b128 v[204:207], v141 offset:52224
	ds_read_b128 v[208:211], v141 offset:53248
	ds_read_b128 v[212:215], v141 offset:54272
	ds_read_b128 v[216:219], v141 offset:55296
	ds_read_b128 v[226:229], v141 offset:56320
	global_load_lds_dwordx4 v[230:231], off
	s_add_i32 m0, s12, 0x2000
	s_add_u32 s10, s10, 0x40080
	v_lshl_add_u64 v[230:231], v[232:233], 0, s[4:5]
	s_addc_u32 s11, s11, 0
	s_add_i32 s12, s77, s19
	global_load_lds_dwordx4 v[230:231], off
	v_lshl_add_u64 v[230:231], s[10:11], 0, v[188:189]
	s_mov_b32 m0, s12
	s_nop 0
	global_load_lds_dwordx4 v[230:231], off
	v_lshl_add_u64 v[230:231], s[10:11], 0, v[130:131]
	s_add_i32 m0, s12, 0x2000
	s_nop 0
	global_load_lds_dwordx4 v[230:231], off
	v_lshl_add_u64 v[230:231], v[234:235], 0, s[4:5]
	s_mov_b32 m0, s37
	s_nop 0
	global_load_lds_dwordx4 v[230:231], off
	v_lshl_add_u64 v[230:231], v[236:237], 0, s[4:5]
	s_mov_b32 m0, s43
	s_nop 0
	global_load_lds_dwordx4 v[230:231], off
	s_waitcnt vmcnt(8)
	s_waitcnt lgkmcnt(0)
	s_barrier
	s_setprio 1
	s_waitcnt lgkmcnt(0)
	v_mfma_f32_16x16x32_bf16 v[106:109], v[142:145], v[178:181], v[106:109]
	v_mfma_f32_16x16x32_bf16 v[82:85], v[150:153], v[178:181], v[82:85]
	v_mfma_f32_16x16x32_bf16 v[110:113], v[142:145], v[200:203], v[110:113]
	v_mfma_f32_16x16x32_bf16 v[86:89], v[150:153], v[200:203], v[86:89]
	v_mfma_f32_16x16x32_bf16 v[102:105], v[142:145], v[208:211], v[102:105]
	v_mfma_f32_16x16x32_bf16 v[90:93], v[150:153], v[208:211], v[90:93]
	v_mfma_f32_16x16x32_bf16 v[98:101], v[142:145], v[216:219], v[98:101]
	v_mfma_f32_16x16x32_bf16 v[94:97], v[150:153], v[216:219], v[94:97]
	v_mfma_f32_16x16x32_bf16 v[106:109], v[146:149], v[182:185], v[106:109]
	v_mfma_f32_16x16x32_bf16 v[82:85], v[154:157], v[182:185], v[82:85]
	v_mfma_f32_16x16x32_bf16 v[110:113], v[146:149], v[204:207], v[110:113]
	v_mfma_f32_16x16x32_bf16 v[86:89], v[154:157], v[204:207], v[86:89]
	v_mfma_f32_16x16x32_bf16 v[102:105], v[146:149], v[212:215], v[102:105]
	v_mfma_f32_16x16x32_bf16 v[90:93], v[154:157], v[212:215], v[90:93]
	v_mfma_f32_16x16x32_bf16 v[98:101], v[146:149], v[226:229], v[98:101]
	v_mfma_f32_16x16x32_bf16 v[94:97], v[154:157], v[226:229], v[94:97]
	s_setprio 0
	s_setprio 1
	v_mfma_f32_16x16x32_bf16 v[50:53], v[158:161], v[178:181], v[50:53]
	v_mfma_f32_16x16x32_bf16 v[18:21], v[170:173], v[178:181], v[18:21]
	v_mfma_f32_16x16x32_bf16 v[54:57], v[158:161], v[200:203], v[54:57]
	v_mfma_f32_16x16x32_bf16 v[22:25], v[170:173], v[200:203], v[22:25]
	v_mfma_f32_16x16x32_bf16 v[58:61], v[158:161], v[208:211], v[58:61]
	v_mfma_f32_16x16x32_bf16 v[26:29], v[170:173], v[208:211], v[26:29]
	v_mfma_f32_16x16x32_bf16 v[62:65], v[158:161], v[216:219], v[62:65]
	v_mfma_f32_16x16x32_bf16 v[30:33], v[170:173], v[216:219], v[30:33]
	v_mfma_f32_16x16x32_bf16 v[50:53], v[162:165], v[182:185], v[50:53]
	v_mfma_f32_16x16x32_bf16 v[18:21], v[174:177], v[182:185], v[18:21]
	v_mfma_f32_16x16x32_bf16 v[54:57], v[162:165], v[204:207], v[54:57]
	v_mfma_f32_16x16x32_bf16 v[22:25], v[174:177], v[204:207], v[22:25]
	v_mfma_f32_16x16x32_bf16 v[58:61], v[162:165], v[212:215], v[58:61]
	v_mfma_f32_16x16x32_bf16 v[26:29], v[174:177], v[212:215], v[26:29]
	v_mfma_f32_16x16x32_bf16 v[62:65], v[162:165], v[226:229], v[62:65]
	v_mfma_f32_16x16x32_bf16 v[30:33], v[174:177], v[226:229], v[30:33]
	s_setprio 0
	s_barrier
	s_add_i32 s70, s70, 2
	s_add_u32 s8, s8, 0x100
	s_addc_u32 s9, s9, 0
	s_cmp_gt_u32 s70, 13
	s_cbranch_scc0 .LBB0_3228
	s_add_u32 s8, s63, 0xffffff00
	s_addc_u32 s9, s64, -1
	s_andn2_b64 vcc, exec, s[40:41]
	s_cbranch_vccnz .LBB0_3219
	v_mov_b32_e32 v30, 0
	s_mov_b32 s42, s56
	s_mov_b32 s16, s58
	s_mov_b64 s[52:53], s[0:1]
	s_mov_b32 s55, s62
	v_mov_b64_e32 v[2:3], 0
	v_mov_b64_e32 v[4:5], 0
	v_mov_b64_e32 v[6:7], 0
	v_mov_b64_e32 v[8:9], 0
	v_mov_b64_e32 v[10:11], 0
	v_mov_b64_e32 v[12:13], 0
	v_mov_b64_e32 v[14:15], 0
	v_mov_b64_e32 v[16:17], 0
	v_mov_b64_e32 v[18:19], 0
	v_mov_b64_e32 v[20:21], 0
	v_mov_b64_e32 v[22:23], 0
	v_mov_b64_e32 v[24:25], 0
	v_mov_b64_e32 v[26:27], 0
	v_mov_b64_e32 v[28:29], 0
	v_mov_b64_e32 v[30:31], 0
	v_mov_b64_e32 v[32:33], 0
	v_mov_b64_e32 v[34:35], 0
	v_mov_b64_e32 v[36:37], 0
	v_mov_b64_e32 v[38:39], 0
	v_mov_b64_e32 v[40:41], 0
	v_mov_b64_e32 v[42:43], 0
	v_mov_b64_e32 v[44:45], 0
	v_mov_b64_e32 v[46:47], 0
	v_mov_b64_e32 v[48:49], 0
	v_mov_b64_e32 v[50:51], 0
	v_mov_b64_e32 v[52:53], 0
	v_mov_b64_e32 v[54:55], 0
	v_mov_b64_e32 v[56:57], 0
	v_mov_b64_e32 v[58:59], 0
	v_mov_b64_e32 v[60:61], 0
	v_mov_b64_e32 v[62:63], 0
	v_mov_b64_e32 v[64:65], 0
	v_mov_b64_e32 v[66:67], 0
	v_mov_b64_e32 v[68:69], 0
	v_mov_b64_e32 v[70:71], 0
	v_mov_b64_e32 v[72:73], 0
	v_mov_b64_e32 v[74:75], 0
	v_mov_b64_e32 v[76:77], 0
	v_mov_b64_e32 v[78:79], 0
	v_mov_b64_e32 v[80:81], 0
	v_mov_b64_e32 v[82:83], 0
	v_mov_b64_e32 v[84:85], 0
	v_mov_b64_e32 v[86:87], 0
	v_mov_b64_e32 v[88:89], 0
	v_mov_b64_e32 v[90:91], 0
	v_mov_b64_e32 v[92:93], 0
	v_mov_b64_e32 v[94:95], 0
	v_mov_b64_e32 v[96:97], 0
	v_mov_b64_e32 v[98:99], 0
	v_mov_b64_e32 v[100:101], 0
	v_mov_b64_e32 v[102:103], 0
	v_mov_b64_e32 v[104:105], 0
	v_mov_b64_e32 v[106:107], 0
	v_mov_b64_e32 v[108:109], 0
	v_mov_b64_e32 v[110:111], 0
	v_mov_b64_e32 v[112:113], 0
	v_mov_b64_e32 v[114:115], 0
	v_mov_b64_e32 v[116:117], 0
	v_mov_b64_e32 v[118:119], 0
	v_mov_b64_e32 v[120:121], 0
	v_mov_b64_e32 v[122:123], 0
	v_mov_b64_e32 v[124:125], 0
	v_mov_b64_e32 v[126:127], 0
	v_mov_b64_e32 v[128:129], 0
	s_mov_b64 s[70:71], 0x20000
	s_andn2_b64 vcc, exec, s[38:39]
	s_cbranch_vccnz .LBB0_3220
